# first polls of the two hidden seam counters prefetched (issued with the preceding write-back / at mixer-B setup): one memory round trip less per workgroup at each
# baseline (speedup 1.0000x reference)
;     __host__ __device__ bool next(int i, Unit& u) const { if (lo + i >= hi) return false; return base.next(lo + i, u); }
; __global__ void __launch_bounds__(NWAVES * 64, 2) mega_fwd(Args a) {
;     ...
;             else { pg8::Unit u7; S.next(6, u7); flag_set(gflag + u7.pm); }
;         }
;     }
;     if (IN(1) && IN(2)) bar_wait(ctr1, (unsigned)G);
.LBB0_160:
	s_waitcnt vmcnt(0)
	s_waitcnt vmcnt(0)
	s_barrier
	s_and_saveexec_b64 s[18:19], s[0:1]
	s_cbranch_execz .LBB0_162
	s_ashr_i32 s17, s16, 31
	s_lshl_b64 s[20:21], s[16:17], 2
	global_load_dword v248, v155, s[76:77] sc1
	buffer_wbl2 sc1
	s_waitcnt vmcnt(0)
	s_add_u32 s20, s76, s20
	s_addc_u32 s21, s77, s21
	global_atomic_add v155, v181, s[76:77] offset:260

; __device__ __forceinline__ void bar_wait(unsigned* ctr, unsigned target) {
;     if (threadIdx.x == 0) { while (__hip_atomic_load(ctr, __ATOMIC_RELAXED, __HIP_MEMORY_SCOPE_AGENT) < target) __builtin_amdgcn_s_sleep(2);
;         __builtin_amdgcn_fence(__ATOMIC_ACQUIRE, "agent"); asm volatile("s_waitcnt vmcnt(0)" ::: "memory"); }
;     __syncthreads();
; }
; __global__ void __launch_bounds__(NWAVES * 64, 2) mega_fwd(Args a) {
;     ...
;     if (IN(1) && IN(2)) bar_wait(ctr1, (unsigned)G);
.LBB0_167:
	s_cmp_gt_i32 s79, 2
	s_cselect_b64 s[0:1], -1, 0
	s_and_b64 s[2:3], s[8:9], s[0:1]
	s_andn2_b64 vcc, exec, s[2:3]
	v_readlane_b32 s16, v254, 16
	v_readlane_b32 s17, v254, 17
	s_cbranch_vccnz .LBB0_173
	v_cmp_eq_u32_e32 vcc, 0, v229
	s_and_saveexec_b64 s[2:3], vcc
	s_cbranch_execz .LBB0_172
	v_mov_b32_e32 v0, 0
	v_cmp_le_u32_e32 vcc, s83, v248
	s_cbranch_vccnz .LBB0_171

; #define LAS __attribute__((address_space(3)))
; __global__ void __launch_bounds__(NWAVES * 64, 2) mega_fwd(Args a) {
;     ...
;         for (int rep_ = 0; rep_ < REP_P2B; ++rep_)
;         for (int i = 0;; ++i) {
;             int u;
;             if (tid == 0) *(volatile LAS unsigned*)((LAS unsigned char*)lds + QSLOT_OFF) = __hip_atomic_fetch_add(qctr, 1u, __ATOMIC_RELAXED, __HIP_MEMORY_SCOPE_AGENT);
;             __syncthreads();
;             u = __builtin_amdgcn_readfirstlane((int)*(volatile LAS unsigned*)((LAS unsigned char*)lds + QSLOT_OFF));
;             if (u >= 1024) break;
;             const int h = u >> 6, b = (u >> 5) & 1, qb = u & 31;
;             if (split7 && h >= 12) flag_wait(gflag + b * 32 + qb);
.LBB0_330:
	s_mov_b32 s90, 0
	v_readlane_b32 s76, v254, 61
	v_readlane_b32 s56, v254, 30
	v_readlane_b32 s77, v254, 62
	v_mov_b32_e32 v243, 0
	s_nop 3
	global_load_dword v242, v243, s[76:77] offset:260 sc1
	s_add_u32 s30, s76, 0x3000800
	v_readlane_b32 s0, v254, 28
	v_readlane_b32 s68, v254, 42
	v_readlane_b32 s69, v254, 43
	s_addc_u32 s33, s77, 0
	v_sub_u32_e32 v0, v232, v238
	s_add_i32 s34, 0, 0x23fc0
	v_readlane_b32 s1, v254, 29
	v_readlane_b32 s58, v254, 32
	v_readlane_b32 s59, v254, 33
	v_readlane_b32 s60, v254, 34
	v_readlane_b32 s61, v254, 35
	v_readlane_b32 s62, v254, 36
	v_readlane_b32 s63, v254, 37
	v_readlane_b32 s64, v254, 38
	v_readlane_b32 s65, v254, 39
	v_readlane_b32 s72, v254, 52
	v_readlane_b32 s68, v254, 56
	s_mov_b32 s7, 0
	v_cmp_eq_u32_e64 s[2:3], 0, v229
	v_readlane_b32 s78, v254, 63
	v_readlane_b32 s79, v255, 0
	v_lshlrev_b32_e32 v194, 8, v231
	v_add_u32_e32 v195, 0xfffffec5, v0
	v_mov_b32_e32 v1, 0
	v_mov_b32_e32 v196, s34
	s_xor_b64 s[8:9], s[0:1], -1
	s_movk_i32 s35, 0x80
	s_movk_i32 s36, 0xff7f
	s_mov_b32 s37, 0x41000000
	s_mov_b32 s38, 0x3fb8aa3b
	v_lshlrev_b32_e32 v197, 1, v228
	v_mov_b32_e32 v198, 0xff800000
	v_readlane_b32 s66, v254, 40
	v_readlane_b32 s67, v254, 41
	v_readlane_b32 s70, v254, 44
	v_readlane_b32 s71, v254, 45
	v_readlane_b32 s73, v254, 53
	v_readlane_b32 s58, v254, 46
	v_readlane_b32 s59, v254, 47
	v_readlane_b32 s60, v254, 22
	v_readlane_b32 s61, v254, 23
	v_readlane_b32 s62, v254, 24
	v_readlane_b32 s63, v254, 25
	v_readlane_b32 s64, v254, 26
	v_readlane_b32 s65, v254, 27
	v_readlane_b32 s69, v254, 57
	v_readlane_b32 s57, v254, 31
	s_branch .LBB0_334

; __device__ __forceinline__ void flag_wait(unsigned* f) {
;     if (threadIdx.x == 0) { while (__hip_atomic_load(f, __ATOMIC_RELAXED, __HIP_MEMORY_SCOPE_AGENT) == 0u) __builtin_amdgcn_s_sleep(2);
;         __builtin_amdgcn_fence(__ATOMIC_ACQUIRE, "agent"); asm volatile("s_waitcnt vmcnt(0)" ::: "memory"); }
;     __syncthreads();
; __global__ void __launch_bounds__(NWAVES * 64, 2) mega_fwd(Args a) {
;     ...
;             if (u >= 1024) break;
;             const int h = u >> 6, b = (u >> 5) & 1, qb = u & 31;
;             if (split7 && h >= 12) flag_wait(gflag + b * 32 + qb);
.LBB0_338:
	s_or_b64 exec, exec, s[0:1]
	s_waitcnt lgkmcnt(0)
	s_barrier
	ds_read_b32 v0, v196
	s_mov_b64 s[0:1], -1
	s_waitcnt lgkmcnt(0)
	v_readfirstlane_b32 s13, v0
	s_cmpk_gt_i32 s13, 0x3ff
	s_cbranch_scc1 .LBB0_333
	s_ashr_i32 s0, s13, 6
	s_bfe_u32 s6, s13, 0x10005
	s_and_b32 s12, s13, 31
	s_cmp_lt_i32 s0, 12
	s_cselect_b64 s[4:5], -1, 0
	s_mov_b64 s[4:5], s[8:9]
	s_and_b64 vcc, exec, s[4:5]
	s_cbranch_vccnz .LBB0_345
	s_cmp_lg_u32 s90, 0
	s_cbranch_scc1 .LBB0_345
	s_and_saveexec_b64 s[4:5], s[2:3]
	s_cbranch_execz .Lfw_join
	s_waitcnt vmcnt(0)
	v_cmp_gt_u32_e32 vcc, s83, v242
	s_cbranch_vccz .Lfw_done
